# v23 plus permlane16/32_swap row-sum reductions in the fused epilogue (no counted waits across flat loads)
# speedup vs baseline: 1.0051x; 1.0051x over previous
; __device__ __forceinline__ void panel_rstd(const f32x4 (&v)[2][2][4][2], const Unit& u, int wr, int wc, int fr, int fq, PG8_LAS unsigned char* lds, int wid, int lane,
;                                            float* xslots, unsigned* cnt, unsigned want, float eps) {
;     ...
;             float s = 0.f;
; #pragma unroll
;             for (int bj = 0; bj < 2; ++bj)
; #pragma unroll
;                 for (int n = 0; n < 2; ++n) { const f32x4 x = v[ai][bj][m][n]; s += (x[0] * x[0] + x[1] * x[1]) + (x[2] * x[2] + x[3] * x[3]); }
;             s += __shfl_xor(s, 16); s += __shfl_xor(s, 32);
;             if (fq == 0) P[(ai * HALF + wr * 64 + m * 16 + fr) * 4 + wc] = s;
;     __device__ __forceinline__ void fused(f32x4 (&acc)[2][2][4][2], const Unit& u, int wr, int wc, int fr, int fq, PG8_LAS unsigned char* lds, int wid, int lane) const {
;     ...
; #pragma unroll
;         for (int ai = 0; ai < 2; ++ai)
; #pragma unroll
;             for (int m = 0; m < 4; ++m)
; #pragma unroll
;                 for (int bj = 0; bj < 2; ++bj) pre[ai][m][bj] = *(const u32x4v*)(X + (size_t)(u.pm * BM + ai * HALF + wr * 64 + m * 16 + fr) * 1024 + col0 + bj * HALF);
;         panel_rstd(acc, u, wr, wc, fr, fq, lds, wid, lane, xbuf, cnt, want1, 1e-6f);
.LBB0_725:
	s_lshl_b32 s0, s26, 5
	s_lshl_b32 s1, s10, 8
	s_lshl_b32 s40, s39, 8
	v_lshrrev_b32_e32 v0, 1, v206
	s_or_b32 s0, s1, s0
	s_add_i32 s4, s40, s33
	v_and_or_b32 v0, v0, 24, s0
	v_readlane_b32 s12, v255, 3
	v_readlane_b32 s28, v255, 7
	v_readlane_b32 s14, v255, 1
	v_readlane_b32 s30, v255, 5
	v_readlane_b32 s0, v252, 50
	v_or_b32_e32 v100, s4, v219
	v_readlane_b32 s13, v255, 4
	v_readlane_b32 s29, v255, 8
	v_readlane_b32 s15, v255, 2
	v_readlane_b32 s31, v255, 6
	v_readlane_b32 s1, v252, 51
	v_ashrrev_i32_e32 v1, 31, v0
	v_ashrrev_i32_e32 v101, 31, v100
	s_barrier
	v_readlane_b32 s22, v253, 6
	v_readlane_b32 s20, v255, 9
	v_readlane_b32 s24, v253, 4
	v_readlane_b32 s18, v255, 11
	v_lshl_add_u64 v[204:205], v[0:1], 1, s[0:1]
	v_lshlrev_b64 v[102:103], 11, v[100:101]
	v_readlane_b32 s23, v253, 7
	v_readlane_b32 s21, v255, 10
	v_readlane_b32 s25, v253, 5
	v_readlane_b32 s41, v255, 36
	v_readlane_b32 s19, v255, 12
	v_lshl_add_u64 v[102:103], v[204:205], 0, v[102:103]
	flat_load_dwordx4 v[192:195], v[102:103]
	flat_load_dwordx4 v[140:143], v[102:103] offset:256
	v_or_b32_e32 v102, 16, v100
	v_ashrrev_i32_e32 v103, 31, v102
	v_lshlrev_b64 v[102:103], 11, v[102:103]
	v_lshl_add_u64 v[102:103], v[204:205], 0, v[102:103]
	flat_load_dwordx4 v[188:191], v[102:103]
	flat_load_dwordx4 v[132:135], v[102:103] offset:256
	v_or_b32_e32 v102, 32, v100
	v_ashrrev_i32_e32 v103, 31, v102
	v_lshlrev_b64 v[102:103], 11, v[102:103]
	v_lshl_add_u64 v[102:103], v[204:205], 0, v[102:103]
	flat_load_dwordx4 v[184:187], v[102:103]
	flat_load_dwordx4 v[128:131], v[102:103] offset:256
	v_or_b32_e32 v102, 48, v100
	v_ashrrev_i32_e32 v103, 31, v102
	v_lshlrev_b64 v[102:103], 11, v[102:103]
	v_lshl_add_u64 v[102:103], v[204:205], 0, v[102:103]
	flat_load_dwordx4 v[180:183], v[102:103]
	flat_load_dwordx4 v[124:127], v[102:103] offset:256
	v_add_u32_e32 v102, 0x80, v100
	v_ashrrev_i32_e32 v103, 31, v102
	v_lshlrev_b64 v[102:103], 11, v[102:103]
	v_lshl_add_u64 v[102:103], v[204:205], 0, v[102:103]
	flat_load_dwordx4 v[176:179], v[102:103]
	flat_load_dwordx4 v[120:123], v[102:103] offset:256
	v_add_u32_e32 v102, 0x90, v100
	v_ashrrev_i32_e32 v103, 31, v102
	v_lshlrev_b64 v[102:103], 11, v[102:103]
	v_lshl_add_u64 v[102:103], v[204:205], 0, v[102:103]
	flat_load_dwordx4 v[172:175], v[102:103]
	flat_load_dwordx4 v[108:111], v[102:103] offset:256
	v_add_u32_e32 v102, 0xa0, v100
	v_add_u32_e32 v100, 0xb0, v100
	v_ashrrev_i32_e32 v103, 31, v102
	v_ashrrev_i32_e32 v101, 31, v100
	v_lshlrev_b64 v[102:103], 11, v[102:103]
	v_lshlrev_b64 v[100:101], 11, v[100:101]
	v_lshl_add_u64 v[102:103], v[204:205], 0, v[102:103]
	v_lshl_add_u64 v[100:101], v[204:205], 0, v[100:101]
	flat_load_dwordx4 v[168:171], v[102:103]
	flat_load_dwordx4 v[104:107], v[102:103] offset:256
	flat_load_dwordx4 v[164:167], v[100:101]
	s_nop 0
	flat_load_dwordx4 v[100:103], v[100:101] offset:256
	v_mul_f32_e32 v207, v97, v97
	v_mul_f32_e32 v208, v99, v99
	v_fmac_f32_e32 v207, v96, v96
	v_fmac_f32_e32 v208, v98, v98
	v_add_f32_e32 v207, v207, v208
	v_mul_f32_e32 v208, v161, v161
	v_mul_f32_e32 v209, v163, v163
	v_fmac_f32_e32 v208, v160, v160
	v_fmac_f32_e32 v209, v162, v162
	v_add_f32_e32 v208, v208, v209
	v_add_f32_e32 v207, v208, v207
	v_mul_f32_e32 v208, v85, v85
	v_mul_f32_e32 v209, v87, v87
	v_fmac_f32_e32 v208, v84, v84
	v_fmac_f32_e32 v209, v86, v86
	v_add_f32_e32 v208, v208, v209
	v_xor_b32_e32 v2, 16, v225
	v_add_f32_e32 v207, v208, v207
	v_mul_f32_e32 v208, v33, v33
	v_mul_f32_e32 v209, v35, v35
	v_cmp_lt_i32_e32 vcc, v2, v230
	v_fmac_f32_e32 v208, v32, v32
	v_fmac_f32_e32 v209, v34, v34
	v_cndmask_b32_e32 v2, v225, v2, vcc
	v_add_f32_e32 v208, v208, v209
	v_lshlrev_b32_e32 v2, 2, v2
	v_add_f32_e32 v207, v208, v207
	v_mov_b32_e32 v208, v207
	s_nop 1
	v_permlane16_swap_b32_e32 v208, v207
	v_xor_b32_e32 v209, 32, v225
	v_cmp_lt_i32_e32 vcc, v209, v230
	s_lshl_b32 s4, s26, 2
	s_add_i32 s48, s4, 0
	v_cndmask_b32_e32 v209, v225, v209, vcc
	v_lshlrev_b32_e32 v221, 2, v209
	s_waitcnt lgkmcnt(0)
	v_add_f32_e32 v207, v207, v208
	v_mov_b32_e32 v209, v207
	s_nop 1
	v_permlane32_swap_b32_e32 v209, v207
	v_and_b32_e32 v208, 63, v206
	v_cmp_gt_u32_e64 s[0:1], 16, v208
	s_and_saveexec_b64 s[4:5], s[0:1]
	s_cbranch_execz .LBB0_727
	s_lshl_b32 s6, s38, 10
	s_add_i32 s6, s48, s6
	v_lshl_add_u32 v210, v219, 4, s6
	s_waitcnt lgkmcnt(0)
	v_add_f32_e32 v207, v207, v209
	ds_write_b32 v210, v207
